# NSA block selection: rank counting via 64-bit (value,index) key compares, 2 VALU per candidate pair instead of 4 VALU + 2 SALU
# speedup vs baseline: 1.0294x; 1.0033x over previous
; DI void nsa_attn_phase(int wv, const P& p_, LAS unsigned char* lds) {
;     ...
;       float mine[8]; int cnt[8];
; #pragma unroll
;       for (int e = 0; e < 8; ++e) { const int j = jj * 8 + e; mine[e] = (j >= 1 && j <= hiJ) ? G4s[tok * 64 + j] : 0.f; cnt[e] = 0; }
;       for (int j2 = 1; j2 <= hiJ; ++j2) { const float v = G4s[tok * 64 + j2];
; #pragma unroll
;         for (int e = 0; e < 8; ++e) { const int j = jj * 8 + e; cnt[e] += (v > mine[e] || (v == mine[e] && j2 < j)) ? 1 : 0; } }
;       unsigned long long bits = 0ull;
; #pragma unroll
;       for (int e = 0; e < 8; ++e) { const int j = jj * 8 + e; if (j >= 1 && j <= hiJ && cnt[e] < 13) bits |= 1ull << j; }
;       if (jj == 0) bits |= 1ull | (1ull << qi) | (1ull << (qi - 1));
.LBB0_746:
	s_and_b32 s36, s41, -2
	v_readlane_b32 s0, v255, 3
	s_waitcnt lgkmcnt(0)
	v_mov_b32_e32 v1, v26
	v_mov_b32_e32 v3, v16
	v_mov_b32_e32 v5, v0
	v_mov_b32_e32 v7, v14
	v_mov_b32_e32 v9, v20
	v_mov_b32_e32 v11, v2
	v_mov_b32_e32 v13, v18
	v_mov_b32_e32 v15, v4
	v_mov_b32_e32 v17, v24
	v_mov_b32_e32 v19, v6
	v_mov_b32_e32 v21, v22
	v_mov_b32_e32 v23, v8
	v_mov_b32_e32 v25, v28
	v_mov_b32_e32 v27, v10
	v_mov_b32_e32 v29, v12
	v_add_u32_e32 v36, s0, v35
	s_mov_b32 s37, 2
	s_mov_b32 s38, 1
	v_mov_b32_e32 v37, 0
	s_mov_b32 s39, s36
	v_mov_b32_e32 v38, 0
	v_mov_b32_e32 v39, 0
	v_mov_b32_e32 v40, 0
	v_mov_b32_e32 v41, 0
	v_mov_b32_e32 v42, 0
	v_mov_b32_e32 v43, 0
	v_mov_b32_e32 v44, 0
	v_mov_b32_e32 v45, 0
	v_mov_b32_e32 v46, 0
	v_mov_b32_e32 v47, 0
	v_mov_b32_e32 v48, 0
	v_mov_b32_e32 v49, 0
	v_mov_b32_e32 v50, 0
	v_mov_b32_e32 v51, 0
	v_mov_b32_e32 v52, 0
	v_sub_u32_e32 v66, 63, v0
	v_mov_b32_e32 v67, v16
	v_sub_u32_e32 v68, 62, v0
	v_mov_b32_e32 v69, v14
	v_sub_u32_e32 v70, 63, v2
	v_mov_b32_e32 v71, v20
	v_sub_u32_e32 v72, 63, v4
	v_mov_b32_e32 v73, v18
	v_sub_u32_e32 v74, 63, v6
	v_mov_b32_e32 v75, v24
	v_sub_u32_e32 v76, 63, v8
	v_mov_b32_e32 v77, v22
	v_sub_u32_e32 v78, 63, v10
	v_mov_b32_e32 v79, v28
	v_sub_u32_e32 v80, 63, v12
	v_mov_b32_e32 v81, v26
.LBB0_747:
	ds_read_b32 v83, v36
	ds_read_b32 v85, v36 offset:4
	s_sub_i32 s0, 63, s38
	s_sub_i32 s1, 63, s37
	v_mov_b32_e32 v82, s0
	v_mov_b32_e32 v84, s1
	s_add_i32 s39, s39, -2
	v_add_u32_e32 v36, 8, v36
	s_waitcnt lgkmcnt(0)
	v_cmp_gt_u64_e64 s[22:23], v[82:83], v[66:67]
	v_cmp_gt_u64_e64 s[24:25], v[84:85], v[66:67]
	v_cmp_gt_u64_e64 s[26:27], v[82:83], v[68:69]
	v_cmp_gt_u64_e64 s[30:31], v[84:85], v[68:69]
	v_addc_co_u32_e64 v51, vcc, 0, v51, s[22:23]
	v_addc_co_u32_e64 v52, vcc, 0, v52, s[24:25]
	v_addc_co_u32_e64 v49, vcc, 0, v49, s[26:27]
	v_addc_co_u32_e64 v50, vcc, 0, v50, s[30:31]
	v_cmp_gt_u64_e64 s[22:23], v[82:83], v[70:71]
	v_cmp_gt_u64_e64 s[24:25], v[84:85], v[70:71]
	v_cmp_gt_u64_e64 s[26:27], v[82:83], v[72:73]
	v_cmp_gt_u64_e64 s[30:31], v[84:85], v[72:73]
	v_addc_co_u32_e64 v47, vcc, 0, v47, s[22:23]
	v_addc_co_u32_e64 v48, vcc, 0, v48, s[24:25]
	v_addc_co_u32_e64 v45, vcc, 0, v45, s[26:27]
	v_addc_co_u32_e64 v46, vcc, 0, v46, s[30:31]
	v_cmp_gt_u64_e64 s[22:23], v[82:83], v[74:75]
	v_cmp_gt_u64_e64 s[24:25], v[84:85], v[74:75]
	v_cmp_gt_u64_e64 s[26:27], v[82:83], v[76:77]
	v_cmp_gt_u64_e64 s[30:31], v[84:85], v[76:77]
	v_addc_co_u32_e64 v43, vcc, 0, v43, s[22:23]
	v_addc_co_u32_e64 v44, vcc, 0, v44, s[24:25]
	v_addc_co_u32_e64 v41, vcc, 0, v41, s[26:27]
	v_addc_co_u32_e64 v42, vcc, 0, v42, s[30:31]
	v_cmp_gt_u64_e64 s[22:23], v[82:83], v[78:79]
	v_cmp_gt_u64_e64 s[24:25], v[84:85], v[78:79]
	v_cmp_gt_u64_e64 s[26:27], v[82:83], v[80:81]
	v_cmp_gt_u64_e64 s[30:31], v[84:85], v[80:81]
	v_addc_co_u32_e64 v39, vcc, 0, v39, s[22:23]
	v_addc_co_u32_e64 v40, vcc, 0, v40, s[24:25]
	v_addc_co_u32_e64 v37, vcc, 0, v37, s[26:27]
	v_addc_co_u32_e64 v38, vcc, 0, v38, s[30:31]
	s_add_i32 s38, s38, 2
	s_add_i32 s37, s37, 2
	s_cmp_lg_u32 s39, 0
	s_cbranch_scc1 .LBB0_747
	s_or_b32 s24, s41, 1
	s_cmp_lg_u32 s41, s36
	v_add_u32_e32 v1, v37, v38
	v_add_u32_e32 v3, v39, v40
	v_add_u32_e32 v5, v41, v42
	v_add_u32_e32 v7, v43, v44
	v_add_u32_e32 v9, v45, v46
	v_add_u32_e32 v11, v47, v48
	v_add_u32_e32 v13, v49, v50
	v_add_u32_e32 v15, v51, v52
	s_cselect_b64 s[0:1], -1, 0
	s_and_b64 vcc, exec, s[0:1]
	s_cbranch_vccnz .LBB0_752
	s_branch .LBB0_754
